# scan loop: chunk barrier moved into step 29 so steps 29-31 prefetch the next chunk (no exposed barrier+LDS latency at chunk boundaries)
# baseline (speedup 1.0000x reference)
; __device__ void scan_block(const Params& P, int sb, unsigned char* lds) {
;     ...
;       for (int s = 0; s < SC_CH; ++s) {
;         f32x4 w4n, k4n, b4n, kh4n, r4n; float vn;
;         if (s + 1 < SC_CH) {
;           const float* qn = q + (s + 1) * SC_STEP;
;           w4n = *(const f32x4*)(qn); k4n = *(const f32x4*)(qn + 64); b4n = *(const f32x4*)(qn + 128); kh4n = *(const f32x4*)(qn + 192); r4n = *(const f32x4*)(qn + 256);
;           vn = qv[(s + 1) * SC_STEP];
;         }
;         __builtin_amdgcn_sched_barrier(0);
;         if (s > 0) {
;           const float y = dpp_allreduce16(ypart);
;           yk = (ks == ((s - 1) & 15)) ? y : yk;
;           if (((s - 1) & 15) == 15) yo[(size_t)(s - 16) * 1024] = yk;
;         }
;         const f32x2 pp = (f32x2){S[0], S[1]} * (f32x2){k4[0], k4[1]} + (f32x2){S[2], S[3]} * (f32x2){k4[2], k4[3]};
;         const f32x4 A = S * w4 + v * kh4;
;         const float ar = dpp_allreduce16(pp.x + pp.y);
;         S = A + ar * b4;
;         const f32x2 yy = (f32x2){S[0], S[1]} * (f32x2){r4[0], r4[1]} + (f32x2){S[2], S[3]} * (f32x2){r4[2], r4[3]};
;         ypart = yy.x + yy.y;
;         if (s + 1 < SC_CH) { w4 = w4n; k4 = k4n; b4 = b4n; kh4 = kh4n; r4 = r4n; v = vn; }
.Lscan_top:
	s_waitcnt lgkmcnt(6)
	v_pk_mul_f32 v[52:53], v[6:7], v[14:15]
	v_pk_mul_f32 v[56:57], v[6:7], v[18:19]
	v_pk_fma_f32 v[52:53], v[4:5], v[12:13], v[52:53]
	v_pk_mul_f32 v[54:55], v[4:5], v[16:17]
	v_add_f32_e32 v52, v52, v53
	ds_read_b128 v[76:79], v9 offset:4288
	ds_read_b128 v[80:83], v9 offset:4032
	v_add_f32_dpp v52, v52, v52 quad_perm:[1,0,3,2] row_mask:0xf bank_mask:0xf bound_ctrl:1
	v_pk_fma_f32 v[56:57], v[22:23], v[24:25], v[56:57] op_sel_hi:[1,0,1]
	v_pk_fma_f32 v[54:55], v[20:21], v[24:25], v[54:55] op_sel_hi:[1,0,1]
	v_add_f32_dpp v52, v52, v52 quad_perm:[2,3,0,1] row_mask:0xf bank_mask:0xf bound_ctrl:1
	ds_read_b128 v[88:91], v9 offset:4800
	ds_read_b32 v94, v10 offset:5312
	v_add_f32_dpp v52, v52, v52 row_half_mirror row_mask:0xf bank_mask:0xf bound_ctrl:1
	s_nop 1
	v_add_f32_dpp v52, v52, v52 row_mirror row_mask:0xf bank_mask:0xf bound_ctrl:1
	v_pk_fma_f32 v[6:7], v[46:47], v[52:53], v[56:57] op_sel_hi:[1,0,1]
	v_pk_fma_f32 v[4:5], v[44:45], v[52:53], v[54:55] op_sel_hi:[1,0,1]
	ds_read_b128 v[96:99], v9 offset:3712
	ds_read_b128 v[108:111], v9 offset:4544
	v_pk_mul_f32 v[52:53], v[6:7], v[62:63]
	v_pk_mul_f32 v[56:57], v[6:7], v[66:67]
	v_pk_fma_f32 v[52:53], v[4:5], v[60:61], v[52:53]
	v_pk_mul_f32 v[54:55], v[4:5], v[64:65]
	v_add_f32_e32 v52, v52, v53
	ds_read_b128 v[12:15], v9 offset:5632
	ds_read_b128 v[16:19], v9 offset:5376
	v_add_f32_dpp v52, v52, v52 quad_perm:[1,0,3,2] row_mask:0xf bank_mask:0xf bound_ctrl:1
	v_pk_fma_f32 v[56:57], v[30:31], v[32:33], v[56:57] op_sel_hi:[1,0,1]
	v_pk_fma_f32 v[54:55], v[28:29], v[32:33], v[54:55] op_sel_hi:[1,0,1]
	v_add_f32_dpp v52, v52, v52 quad_perm:[2,3,0,1] row_mask:0xf bank_mask:0xf bound_ctrl:1
	ds_read_b128 v[20:23], v9 offset:6144
	ds_read_b32 v24, v10 offset:6656
	v_add_f32_dpp v52, v52, v52 row_half_mirror row_mask:0xf bank_mask:0xf bound_ctrl:1
	v_pk_mul_f32 v[26:27], v[6:7], v[38:39]
	s_nop 0
	v_add_f32_dpp v52, v52, v52 row_mirror row_mask:0xf bank_mask:0xf bound_ctrl:1
	v_pk_fma_f32 v[6:7], v[50:51], v[52:53], v[56:57] op_sel_hi:[1,0,1]
	v_pk_fma_f32 v[26:27], v[4:5], v[36:37], v[26:27]
	v_pk_fma_f32 v[4:5], v[48:49], v[52:53], v[54:55] op_sel_hi:[1,0,1]
	ds_read_b128 v[100:103], v9 offset:5056
	ds_read_b128 v[44:47], v9 offset:5888
	v_add_f32_e32 v25, v26, v27
	s_waitcnt lgkmcnt(6)
	v_pk_mul_f32 v[52:53], v[6:7], v[70:71]
	v_pk_mul_f32 v[56:57], v[6:7], v[74:75]
	v_pk_fma_f32 v[52:53], v[4:5], v[68:69], v[52:53]
	v_pk_mul_f32 v[54:55], v[4:5], v[72:73]
	v_add_f32_e32 v52, v52, v53
	ds_read_b128 v[60:63], v9 offset:6976
	ds_read_b128 v[64:67], v9 offset:6720
	v_add_f32_dpp v52, v52, v52 quad_perm:[1,0,3,2] row_mask:0xf bank_mask:0xf bound_ctrl:1
	v_pk_fma_f32 v[56:57], v[86:87], v[92:93], v[56:57] op_sel_hi:[1,0,1]
	v_pk_fma_f32 v[54:55], v[84:85], v[92:93], v[54:55] op_sel_hi:[1,0,1]
	v_add_f32_dpp v52, v52, v52 quad_perm:[2,3,0,1] row_mask:0xf bank_mask:0xf bound_ctrl:1
	ds_read_b128 v[28:31], v9 offset:7488
	ds_read_b32 v32, v10 offset:8000
	v_add_f32_dpp v52, v52, v52 row_half_mirror row_mask:0xf bank_mask:0xf bound_ctrl:1
	v_pk_mul_f32 v[26:27], v[6:7], v[42:43]
	v_add_f32_dpp v34, v25, v25 row_ror:8 row_mask:0xf bank_mask:0x3
	v_add_f32_dpp v52, v52, v52 row_mirror row_mask:0xf bank_mask:0xf bound_ctrl:1
	v_pk_fma_f32 v[6:7], v[106:107], v[52:53], v[56:57] op_sel_hi:[1,0,1]
	v_pk_fma_f32 v[26:27], v[4:5], v[40:41], v[26:27]
	v_pk_fma_f32 v[4:5], v[104:105], v[52:53], v[54:55] op_sel_hi:[1,0,1]
	ds_read_b128 v[36:39], v9 offset:6400
	ds_read_b128 v[48:51], v9 offset:7232
	v_add_f32_e32 v25, v26, v27
	v_pk_mul_f32 v[52:53], v[6:7], v[78:79]
	v_pk_mul_f32 v[56:57], v[6:7], v[82:83]
	v_pk_fma_f32 v[52:53], v[4:5], v[76:77], v[52:53]
	v_pk_mul_f32 v[54:55], v[4:5], v[80:81]
	v_add_f32_e32 v52, v52, v53
	ds_read_b128 v[68:71], v9 offset:8320
	ds_read_b128 v[72:75], v9 offset:8064
	v_add_f32_dpp v52, v52, v52 quad_perm:[1,0,3,2] row_mask:0xf bank_mask:0xf bound_ctrl:1
	v_pk_fma_f32 v[56:57], v[90:91], v[94:95], v[56:57] op_sel_hi:[1,0,1]
	v_pk_fma_f32 v[54:55], v[88:89], v[94:95], v[54:55] op_sel_hi:[1,0,1]
	v_add_f32_dpp v52, v52, v52 quad_perm:[2,3,0,1] row_mask:0xf bank_mask:0xf bound_ctrl:1
	ds_read_b128 v[84:87], v9 offset:8832
	ds_read_b32 v92, v10 offset:9344
	v_add_f32_dpp v52, v52, v52 row_half_mirror row_mask:0xf bank_mask:0xf bound_ctrl:1
	v_pk_mul_f32 v[26:27], v[6:7], v[98:99]
	v_add_f32_dpp v34, v25, v25 row_ror:8 row_mask:0xf bank_mask:0xc
	v_add_f32_dpp v52, v52, v52 row_mirror row_mask:0xf bank_mask:0xf bound_ctrl:1
	v_pk_fma_f32 v[6:7], v[110:111], v[52:53], v[56:57] op_sel_hi:[1,0,1]
	v_pk_fma_f32 v[26:27], v[4:5], v[96:97], v[26:27]
	v_pk_fma_f32 v[4:5], v[108:109], v[52:53], v[54:55] op_sel_hi:[1,0,1]
	ds_read_b128 v[40:43], v9 offset:7744
	ds_read_b128 v[104:107], v9 offset:8576
	v_add_f32_e32 v25, v26, v27
	v_add_f32_dpp v35, v34, v34 row_half_mirror row_mask:0xf bank_mask:0x5
	s_waitcnt lgkmcnt(6)
; __device__ void scan_block(const Params& P, int sb, unsigned char* lds) {
;     ...
;       for (int s = 0; s < SC_CH; ++s) {
;         f32x4 w4n, k4n, b4n, kh4n, r4n; float vn;
;         if (s + 1 < SC_CH) {
;           const float* qn = q + (s + 1) * SC_STEP;
;           w4n = *(const f32x4*)(qn); k4n = *(const f32x4*)(qn + 64); b4n = *(const f32x4*)(qn + 128); kh4n = *(const f32x4*)(qn + 192); r4n = *(const f32x4*)(qn + 256);
;           vn = qv[(s + 1) * SC_STEP];
;         }
;         __builtin_amdgcn_sched_barrier(0);
;         if (s > 0) {
;           const float y = dpp_allreduce16(ypart);
;           yk = (ks == ((s - 1) & 15)) ? y : yk;
;           if (((s - 1) & 15) == 15) yo[(size_t)(s - 16) * 1024] = yk;
;         }
;         const f32x2 pp = (f32x2){S[0], S[1]} * (f32x2){k4[0], k4[1]} + (f32x2){S[2], S[3]} * (f32x2){k4[2], k4[3]};
;         const f32x4 A = S * w4 + v * kh4;
;         const float ar = dpp_allreduce16(pp.x + pp.y);
;         S = A + ar * b4;
;         const f32x2 yy = (f32x2){S[0], S[1]} * (f32x2){r4[0], r4[1]} + (f32x2){S[2], S[3]} * (f32x2){r4[2], r4[3]};
;         ypart = yy.x + yy.y;
;         if (s + 1 < SC_CH) { w4 = w4n; k4 = k4n; b4 = b4n; kh4 = kh4n; r4 = r4n; v = vn; }
	v_pk_mul_f32 v[52:53], v[6:7], v[14:15]
	v_pk_mul_f32 v[56:57], v[6:7], v[18:19]
	v_pk_fma_f32 v[52:53], v[4:5], v[12:13], v[52:53]
	v_pk_mul_f32 v[54:55], v[4:5], v[16:17]
	v_add_f32_e32 v52, v52, v53
	ds_read_b128 v[76:79], v9 offset:9664
	ds_read_b128 v[80:83], v9 offset:9408
	v_add_f32_dpp v52, v52, v52 quad_perm:[1,0,3,2] row_mask:0xf bank_mask:0xf bound_ctrl:1
	v_pk_fma_f32 v[56:57], v[22:23], v[24:25], v[56:57] op_sel_hi:[1,0,1]
	v_pk_fma_f32 v[54:55], v[20:21], v[24:25], v[54:55] op_sel_hi:[1,0,1]
	v_add_f32_dpp v52, v52, v52 quad_perm:[2,3,0,1] row_mask:0xf bank_mask:0xf bound_ctrl:1
	ds_read_b128 v[88:91], v9 offset:10176
	ds_read_b32 v94, v10 offset:10688
	v_add_f32_dpp v52, v52, v52 row_half_mirror row_mask:0xf bank_mask:0xf bound_ctrl:1
	v_pk_mul_f32 v[26:27], v[6:7], v[102:103]
	v_add_f32_dpp v34, v25, v25 row_ror:8 row_mask:0xf bank_mask:0x3
	v_add_f32_dpp v52, v52, v52 row_mirror row_mask:0xf bank_mask:0xf bound_ctrl:1
	v_pk_fma_f32 v[6:7], v[46:47], v[52:53], v[56:57] op_sel_hi:[1,0,1]
	v_pk_fma_f32 v[26:27], v[4:5], v[100:101], v[26:27]
	v_pk_fma_f32 v[4:5], v[44:45], v[52:53], v[54:55] op_sel_hi:[1,0,1]
	ds_read_b128 v[96:99], v9 offset:9088
	ds_read_b128 v[108:111], v9 offset:9920
	v_add_f32_e32 v25, v26, v27
	v_pk_mul_f32 v[52:53], v[6:7], v[62:63]
	v_pk_mul_f32 v[56:57], v[6:7], v[66:67]
	v_pk_fma_f32 v[52:53], v[4:5], v[60:61], v[52:53]
	v_pk_mul_f32 v[54:55], v[4:5], v[64:65]
	v_add_f32_e32 v52, v52, v53
	ds_read_b128 v[12:15], v9 offset:11008
	ds_read_b128 v[16:19], v9 offset:10752
	v_add_f32_dpp v52, v52, v52 quad_perm:[1,0,3,2] row_mask:0xf bank_mask:0xf bound_ctrl:1
	v_pk_fma_f32 v[56:57], v[30:31], v[32:33], v[56:57] op_sel_hi:[1,0,1]
	v_pk_fma_f32 v[54:55], v[28:29], v[32:33], v[54:55] op_sel_hi:[1,0,1]
	v_add_f32_dpp v52, v52, v52 quad_perm:[2,3,0,1] row_mask:0xf bank_mask:0xf bound_ctrl:1
	ds_read_b128 v[20:23], v9 offset:11520
	ds_read_b32 v24, v10 offset:12032
	v_add_f32_dpp v52, v52, v52 row_half_mirror row_mask:0xf bank_mask:0xf bound_ctrl:1
	v_pk_mul_f32 v[26:27], v[6:7], v[38:39]
	v_add_f32_dpp v34, v25, v25 row_ror:8 row_mask:0xf bank_mask:0xc
	v_add_f32_dpp v52, v52, v52 row_mirror row_mask:0xf bank_mask:0xf bound_ctrl:1
	v_pk_fma_f32 v[6:7], v[50:51], v[52:53], v[56:57] op_sel_hi:[1,0,1]
	v_pk_fma_f32 v[26:27], v[4:5], v[36:37], v[26:27]
	v_pk_fma_f32 v[4:5], v[48:49], v[52:53], v[54:55] op_sel_hi:[1,0,1]
	ds_read_b128 v[100:103], v9 offset:10432
	ds_read_b128 v[44:47], v9 offset:11264
	v_add_f32_e32 v25, v26, v27
	v_add_f32_dpp v35, v34, v34 row_half_mirror row_mask:0xf bank_mask:0xa
	s_waitcnt lgkmcnt(6)
	v_pk_mul_f32 v[52:53], v[6:7], v[70:71]
	v_pk_mul_f32 v[56:57], v[6:7], v[74:75]
	v_pk_fma_f32 v[52:53], v[4:5], v[68:69], v[52:53]
	v_pk_mul_f32 v[54:55], v[4:5], v[72:73]
	v_add_f32_e32 v52, v52, v53
	ds_read_b128 v[60:63], v9 offset:12352
	ds_read_b128 v[64:67], v9 offset:12096
	v_add_f32_dpp v52, v52, v52 quad_perm:[1,0,3,2] row_mask:0xf bank_mask:0xf bound_ctrl:1
	v_pk_fma_f32 v[56:57], v[86:87], v[92:93], v[56:57] op_sel_hi:[1,0,1]
	v_pk_fma_f32 v[54:55], v[84:85], v[92:93], v[54:55] op_sel_hi:[1,0,1]
	v_add_f32_dpp v52, v52, v52 quad_perm:[2,3,0,1] row_mask:0xf bank_mask:0xf bound_ctrl:1
	ds_read_b128 v[28:31], v9 offset:12864
	ds_read_b32 v32, v10 offset:13376
	v_add_f32_dpp v52, v52, v52 row_half_mirror row_mask:0xf bank_mask:0xf bound_ctrl:1
	v_pk_mul_f32 v[26:27], v[6:7], v[42:43]
	v_add_f32_dpp v34, v25, v25 row_ror:8 row_mask:0xf bank_mask:0x3
	v_add_f32_dpp v52, v52, v52 row_mirror row_mask:0xf bank_mask:0xf bound_ctrl:1
	v_pk_fma_f32 v[6:7], v[106:107], v[52:53], v[56:57] op_sel_hi:[1,0,1]
	v_pk_fma_f32 v[26:27], v[4:5], v[40:41], v[26:27]
	v_pk_fma_f32 v[4:5], v[104:105], v[52:53], v[54:55] op_sel_hi:[1,0,1]
	ds_read_b128 v[36:39], v9 offset:11776
	ds_read_b128 v[48:51], v9 offset:12608
	v_add_f32_e32 v25, v26, v27
	v_pk_mul_f32 v[52:53], v[6:7], v[78:79]
	v_pk_mul_f32 v[56:57], v[6:7], v[82:83]
	v_pk_fma_f32 v[52:53], v[4:5], v[76:77], v[52:53]
	v_pk_mul_f32 v[54:55], v[4:5], v[80:81]
	v_add_f32_e32 v52, v52, v53
	ds_read_b128 v[68:71], v9 offset:13696
	ds_read_b128 v[72:75], v9 offset:13440
	v_add_f32_dpp v52, v52, v52 quad_perm:[1,0,3,2] row_mask:0xf bank_mask:0xf bound_ctrl:1
	v_pk_fma_f32 v[56:57], v[90:91], v[94:95], v[56:57] op_sel_hi:[1,0,1]
	v_pk_fma_f32 v[54:55], v[88:89], v[94:95], v[54:55] op_sel_hi:[1,0,1]
	v_add_f32_dpp v52, v52, v52 quad_perm:[2,3,0,1] row_mask:0xf bank_mask:0xf bound_ctrl:1
	ds_read_b128 v[84:87], v9 offset:14208
	ds_read_b32 v92, v10 offset:14720
	v_add_f32_dpp v52, v52, v52 row_half_mirror row_mask:0xf bank_mask:0xf bound_ctrl:1
	v_pk_mul_f32 v[26:27], v[6:7], v[98:99]
	v_add_f32_dpp v34, v25, v25 row_ror:8 row_mask:0xf bank_mask:0xc
	v_add_f32_dpp v52, v52, v52 row_mirror row_mask:0xf bank_mask:0xf bound_ctrl:1
	v_pk_fma_f32 v[6:7], v[110:111], v[52:53], v[56:57] op_sel_hi:[1,0,1]
	v_pk_fma_f32 v[26:27], v[4:5], v[96:97], v[26:27]
	v_pk_fma_f32 v[4:5], v[108:109], v[52:53], v[54:55] op_sel_hi:[1,0,1]
	ds_read_b128 v[40:43], v9 offset:13120
	ds_read_b128 v[104:107], v9 offset:13952
	v_add_f32_e32 v25, v26, v27
	v_add_f32_dpp v58, v34, v34 row_half_mirror row_mask:0xf bank_mask:0x5
	s_waitcnt lgkmcnt(6)
; __device__ void scan_block(const Params& P, int sb, unsigned char* lds) {
;     ...
;       for (int s = 0; s < SC_CH; ++s) {
;         f32x4 w4n, k4n, b4n, kh4n, r4n; float vn;
;         if (s + 1 < SC_CH) {
;           const float* qn = q + (s + 1) * SC_STEP;
;           w4n = *(const f32x4*)(qn); k4n = *(const f32x4*)(qn + 64); b4n = *(const f32x4*)(qn + 128); kh4n = *(const f32x4*)(qn + 192); r4n = *(const f32x4*)(qn + 256);
;           vn = qv[(s + 1) * SC_STEP];
;         }
;         __builtin_amdgcn_sched_barrier(0);
;         if (s > 0) {
;           const float y = dpp_allreduce16(ypart);
;           yk = (ks == ((s - 1) & 15)) ? y : yk;
;           if (((s - 1) & 15) == 15) yo[(size_t)(s - 16) * 1024] = yk;
;         }
;         const f32x2 pp = (f32x2){S[0], S[1]} * (f32x2){k4[0], k4[1]} + (f32x2){S[2], S[3]} * (f32x2){k4[2], k4[3]};
;         const f32x4 A = S * w4 + v * kh4;
;         const float ar = dpp_allreduce16(pp.x + pp.y);
;         S = A + ar * b4;
;         const f32x2 yy = (f32x2){S[0], S[1]} * (f32x2){r4[0], r4[1]} + (f32x2){S[2], S[3]} * (f32x2){r4[2], r4[3]};
;         ypart = yy.x + yy.y;
;         if (s + 1 < SC_CH) { w4 = w4n; k4 = k4n; b4 = b4n; kh4 = kh4n; r4 = r4n; v = vn; }
	v_pk_mul_f32 v[52:53], v[6:7], v[14:15]
	v_pk_mul_f32 v[56:57], v[6:7], v[18:19]
	v_pk_fma_f32 v[52:53], v[4:5], v[12:13], v[52:53]
	v_pk_mul_f32 v[54:55], v[4:5], v[16:17]
	v_add_f32_e32 v52, v52, v53
	ds_read_b128 v[76:79], v9 offset:15040
	ds_read_b128 v[80:83], v9 offset:14784
	v_add_f32_dpp v52, v52, v52 quad_perm:[1,0,3,2] row_mask:0xf bank_mask:0xf bound_ctrl:1
	v_pk_fma_f32 v[56:57], v[22:23], v[24:25], v[56:57] op_sel_hi:[1,0,1]
	v_pk_fma_f32 v[54:55], v[20:21], v[24:25], v[54:55] op_sel_hi:[1,0,1]
	v_add_f32_dpp v52, v52, v52 quad_perm:[2,3,0,1] row_mask:0xf bank_mask:0xf bound_ctrl:1
	ds_read_b128 v[88:91], v9 offset:15552
	ds_read_b32 v94, v10 offset:16064
	v_add_f32_dpp v52, v52, v52 row_half_mirror row_mask:0xf bank_mask:0xf bound_ctrl:1
	v_pk_mul_f32 v[26:27], v[6:7], v[102:103]
	v_add_f32_dpp v34, v25, v25 row_ror:8 row_mask:0xf bank_mask:0x3
	v_add_f32_dpp v52, v52, v52 row_mirror row_mask:0xf bank_mask:0xf bound_ctrl:1
	v_pk_fma_f32 v[6:7], v[46:47], v[52:53], v[56:57] op_sel_hi:[1,0,1]
	v_pk_fma_f32 v[26:27], v[4:5], v[100:101], v[26:27]
	v_pk_fma_f32 v[4:5], v[44:45], v[52:53], v[54:55] op_sel_hi:[1,0,1]
	ds_read_b128 v[96:99], v9 offset:14464
	ds_read_b128 v[108:111], v9 offset:15296
	v_add_f32_e32 v25, v26, v27
	v_pk_mul_f32 v[52:53], v[6:7], v[62:63]
	v_pk_mul_f32 v[56:57], v[6:7], v[66:67]
	v_pk_fma_f32 v[52:53], v[4:5], v[60:61], v[52:53]
	v_pk_mul_f32 v[54:55], v[4:5], v[64:65]
	v_add_f32_e32 v52, v52, v53
	ds_read_b128 v[12:15], v9 offset:16384
	ds_read_b128 v[16:19], v9 offset:16128
	v_add_f32_dpp v52, v52, v52 quad_perm:[1,0,3,2] row_mask:0xf bank_mask:0xf bound_ctrl:1
	v_pk_fma_f32 v[56:57], v[30:31], v[32:33], v[56:57] op_sel_hi:[1,0,1]
	v_pk_fma_f32 v[54:55], v[28:29], v[32:33], v[54:55] op_sel_hi:[1,0,1]
	v_add_f32_dpp v52, v52, v52 quad_perm:[2,3,0,1] row_mask:0xf bank_mask:0xf bound_ctrl:1
	ds_read_b128 v[20:23], v9 offset:16896
	ds_read_b32 v24, v10 offset:17408
	v_add_f32_dpp v52, v52, v52 row_half_mirror row_mask:0xf bank_mask:0xf bound_ctrl:1
	v_pk_mul_f32 v[26:27], v[6:7], v[38:39]
	v_add_f32_dpp v34, v25, v25 row_ror:8 row_mask:0xf bank_mask:0xc
	v_add_f32_dpp v52, v52, v52 row_mirror row_mask:0xf bank_mask:0xf bound_ctrl:1
	v_pk_fma_f32 v[6:7], v[50:51], v[52:53], v[56:57] op_sel_hi:[1,0,1]
	v_pk_fma_f32 v[26:27], v[4:5], v[36:37], v[26:27]
	v_pk_fma_f32 v[4:5], v[48:49], v[52:53], v[54:55] op_sel_hi:[1,0,1]
	ds_read_b128 v[100:103], v9 offset:15808
	ds_read_b128 v[44:47], v9 offset:16640
	v_add_f32_e32 v25, v26, v27
	v_add_f32_dpp v58, v34, v34 row_half_mirror row_mask:0xf bank_mask:0xa
	s_waitcnt lgkmcnt(6)
	v_pk_mul_f32 v[52:53], v[6:7], v[70:71]
	v_pk_mul_f32 v[56:57], v[6:7], v[74:75]
	v_pk_fma_f32 v[52:53], v[4:5], v[68:69], v[52:53]
	v_pk_mul_f32 v[54:55], v[4:5], v[72:73]
	v_add_f32_e32 v52, v52, v53
	ds_read_b128 v[60:63], v9 offset:17728
	ds_read_b128 v[64:67], v9 offset:17472
	v_add_f32_dpp v52, v52, v52 quad_perm:[1,0,3,2] row_mask:0xf bank_mask:0xf bound_ctrl:1
	v_pk_fma_f32 v[56:57], v[86:87], v[92:93], v[56:57] op_sel_hi:[1,0,1]
	v_pk_fma_f32 v[54:55], v[84:85], v[92:93], v[54:55] op_sel_hi:[1,0,1]
	v_add_f32_dpp v52, v52, v52 quad_perm:[2,3,0,1] row_mask:0xf bank_mask:0xf bound_ctrl:1
	ds_read_b128 v[28:31], v9 offset:18240
	ds_read_b32 v32, v10 offset:18752
	v_add_f32_dpp v52, v52, v52 row_half_mirror row_mask:0xf bank_mask:0xf bound_ctrl:1
	v_pk_mul_f32 v[26:27], v[6:7], v[42:43]
	v_add_f32_dpp v34, v25, v25 row_ror:8 row_mask:0xf bank_mask:0x3
	v_add_f32_dpp v52, v52, v52 row_mirror row_mask:0xf bank_mask:0xf bound_ctrl:1
	v_pk_fma_f32 v[6:7], v[106:107], v[52:53], v[56:57] op_sel_hi:[1,0,1]
	v_pk_fma_f32 v[26:27], v[4:5], v[40:41], v[26:27]
	v_pk_fma_f32 v[4:5], v[104:105], v[52:53], v[54:55] op_sel_hi:[1,0,1]
	ds_read_b128 v[36:39], v9 offset:17152
	ds_read_b128 v[48:51], v9 offset:17984
	v_add_f32_e32 v25, v26, v27
	v_cndmask_b32_e64 v255, v35, v58, s[40:41]
	v_pk_mul_f32 v[52:53], v[6:7], v[78:79]
	v_pk_mul_f32 v[56:57], v[6:7], v[82:83]
	v_pk_fma_f32 v[52:53], v[4:5], v[76:77], v[52:53]
	v_pk_mul_f32 v[54:55], v[4:5], v[80:81]
	v_add_f32_e32 v52, v52, v53
	ds_read_b128 v[68:71], v9 offset:19072
	ds_read_b128 v[72:75], v9 offset:18816
	v_add_f32_dpp v52, v52, v52 quad_perm:[1,0,3,2] row_mask:0xf bank_mask:0xf bound_ctrl:1
	v_pk_fma_f32 v[56:57], v[90:91], v[94:95], v[56:57] op_sel_hi:[1,0,1]
	v_pk_fma_f32 v[54:55], v[88:89], v[94:95], v[54:55] op_sel_hi:[1,0,1]
	v_add_f32_dpp v52, v52, v52 quad_perm:[2,3,0,1] row_mask:0xf bank_mask:0xf bound_ctrl:1
	ds_read_b128 v[84:87], v9 offset:19584
	ds_read_b32 v92, v10 offset:20096
	v_add_f32_dpp v52, v52, v52 row_half_mirror row_mask:0xf bank_mask:0xf bound_ctrl:1
	v_pk_mul_f32 v[26:27], v[6:7], v[98:99]
	v_add_f32_dpp v34, v25, v25 row_ror:8 row_mask:0xf bank_mask:0xc
	v_add_f32_dpp v52, v52, v52 row_mirror row_mask:0xf bank_mask:0xf bound_ctrl:1
	v_pk_fma_f32 v[6:7], v[110:111], v[52:53], v[56:57] op_sel_hi:[1,0,1]
	v_pk_fma_f32 v[26:27], v[4:5], v[96:97], v[26:27]
	v_pk_fma_f32 v[4:5], v[108:109], v[52:53], v[54:55] op_sel_hi:[1,0,1]
	ds_read_b128 v[40:43], v9 offset:18496
	ds_read_b128 v[104:107], v9 offset:19328
	v_add_f32_e32 v25, v26, v27
	v_add_f32_dpp v0, v34, v34 row_half_mirror row_mask:0xf bank_mask:0x5
	s_waitcnt lgkmcnt(6)
; __device__ void scan_block(const Params& P, int sb, unsigned char* lds) {
;     ...
;       for (int s = 0; s < SC_CH; ++s) {
;         f32x4 w4n, k4n, b4n, kh4n, r4n; float vn;
;         if (s + 1 < SC_CH) {
;           const float* qn = q + (s + 1) * SC_STEP;
;           w4n = *(const f32x4*)(qn); k4n = *(const f32x4*)(qn + 64); b4n = *(const f32x4*)(qn + 128); kh4n = *(const f32x4*)(qn + 192); r4n = *(const f32x4*)(qn + 256);
;           vn = qv[(s + 1) * SC_STEP];
;         }
;         __builtin_amdgcn_sched_barrier(0);
;         if (s > 0) {
;           const float y = dpp_allreduce16(ypart);
;           yk = (ks == ((s - 1) & 15)) ? y : yk;
;           if (((s - 1) & 15) == 15) yo[(size_t)(s - 16) * 1024] = yk;
;         }
;         const f32x2 pp = (f32x2){S[0], S[1]} * (f32x2){k4[0], k4[1]} + (f32x2){S[2], S[3]} * (f32x2){k4[2], k4[3]};
;         const f32x4 A = S * w4 + v * kh4;
;         const float ar = dpp_allreduce16(pp.x + pp.y);
;         S = A + ar * b4;
;         const f32x2 yy = (f32x2){S[0], S[1]} * (f32x2){r4[0], r4[1]} + (f32x2){S[2], S[3]} * (f32x2){r4[2], r4[3]};
;         ypart = yy.x + yy.y;
;         if (s + 1 < SC_CH) { w4 = w4n; k4 = k4n; b4 = b4n; kh4 = kh4n; r4 = r4n; v = vn; }
	v_pk_mul_f32 v[52:53], v[6:7], v[14:15]
	v_pk_mul_f32 v[56:57], v[6:7], v[18:19]
	v_pk_fma_f32 v[52:53], v[4:5], v[12:13], v[52:53]
	v_pk_mul_f32 v[54:55], v[4:5], v[16:17]
	v_add_f32_e32 v52, v52, v53
	ds_read_b128 v[76:79], v9 offset:20416
	ds_read_b128 v[80:83], v9 offset:20160
	v_add_f32_dpp v52, v52, v52 quad_perm:[1,0,3,2] row_mask:0xf bank_mask:0xf bound_ctrl:1
	v_pk_fma_f32 v[56:57], v[22:23], v[24:25], v[56:57] op_sel_hi:[1,0,1]
	v_pk_fma_f32 v[54:55], v[20:21], v[24:25], v[54:55] op_sel_hi:[1,0,1]
	v_add_f32_dpp v52, v52, v52 quad_perm:[2,3,0,1] row_mask:0xf bank_mask:0xf bound_ctrl:1
	ds_read_b128 v[88:91], v9 offset:20928
	ds_read_b32 v94, v10 offset:21440
	v_add_f32_dpp v52, v52, v52 row_half_mirror row_mask:0xf bank_mask:0xf bound_ctrl:1
	v_pk_mul_f32 v[26:27], v[6:7], v[102:103]
	v_add_f32_dpp v34, v25, v25 row_ror:8 row_mask:0xf bank_mask:0x3
	v_add_f32_dpp v52, v52, v52 row_mirror row_mask:0xf bank_mask:0xf bound_ctrl:1
	v_pk_fma_f32 v[6:7], v[46:47], v[52:53], v[56:57] op_sel_hi:[1,0,1]
	v_pk_fma_f32 v[26:27], v[4:5], v[100:101], v[26:27]
	v_pk_fma_f32 v[4:5], v[44:45], v[52:53], v[54:55] op_sel_hi:[1,0,1]
	ds_read_b128 v[96:99], v9 offset:19840
	ds_read_b128 v[108:111], v9 offset:20672
	v_add_f32_e32 v25, v26, v27
	v_cndmask_b32_e64 v8, v58, v35, s[40:41]
	v_pk_mul_f32 v[52:53], v[6:7], v[62:63]
	v_pk_mul_f32 v[56:57], v[6:7], v[66:67]
	v_pk_fma_f32 v[52:53], v[4:5], v[60:61], v[52:53]
	v_pk_mul_f32 v[54:55], v[4:5], v[64:65]
	v_add_f32_e32 v52, v52, v53
	ds_read_b128 v[12:15], v9 offset:21760
	ds_read_b128 v[16:19], v9 offset:21504
	v_add_f32_dpp v52, v52, v52 quad_perm:[1,0,3,2] row_mask:0xf bank_mask:0xf bound_ctrl:1
	v_pk_fma_f32 v[56:57], v[30:31], v[32:33], v[56:57] op_sel_hi:[1,0,1]
	v_pk_fma_f32 v[54:55], v[28:29], v[32:33], v[54:55] op_sel_hi:[1,0,1]
	v_add_f32_dpp v52, v52, v52 quad_perm:[2,3,0,1] row_mask:0xf bank_mask:0xf bound_ctrl:1
	ds_read_b128 v[20:23], v9 offset:22272
	ds_read_b32 v24, v10 offset:22784
	v_add_f32_dpp v52, v52, v52 row_half_mirror row_mask:0xf bank_mask:0xf bound_ctrl:1
	v_pk_mul_f32 v[26:27], v[6:7], v[38:39]
	v_add_f32_dpp v34, v25, v25 row_ror:8 row_mask:0xf bank_mask:0xc
	v_add_f32_dpp v52, v52, v52 row_mirror row_mask:0xf bank_mask:0xf bound_ctrl:1
	v_pk_fma_f32 v[6:7], v[50:51], v[52:53], v[56:57] op_sel_hi:[1,0,1]
	v_pk_fma_f32 v[26:27], v[4:5], v[36:37], v[26:27]
	v_pk_fma_f32 v[4:5], v[48:49], v[52:53], v[54:55] op_sel_hi:[1,0,1]
	ds_read_b128 v[100:103], v9 offset:21184
	ds_read_b128 v[44:47], v9 offset:22016
	v_add_f32_e32 v25, v26, v27
	v_add_f32_dpp v0, v34, v34 row_half_mirror row_mask:0xf bank_mask:0xa
	s_waitcnt lgkmcnt(6)
	v_pk_mul_f32 v[52:53], v[6:7], v[70:71]
	v_pk_mul_f32 v[56:57], v[6:7], v[74:75]
	v_pk_fma_f32 v[52:53], v[4:5], v[68:69], v[52:53]
	v_pk_mul_f32 v[54:55], v[4:5], v[72:73]
	v_add_f32_e32 v52, v52, v53
	ds_read_b128 v[60:63], v9 offset:23104
	ds_read_b128 v[64:67], v9 offset:22848
	v_add_f32_dpp v52, v52, v52 quad_perm:[1,0,3,2] row_mask:0xf bank_mask:0xf bound_ctrl:1
	v_pk_fma_f32 v[56:57], v[86:87], v[92:93], v[56:57] op_sel_hi:[1,0,1]
	v_pk_fma_f32 v[54:55], v[84:85], v[92:93], v[54:55] op_sel_hi:[1,0,1]
	v_add_f32_dpp v52, v52, v52 quad_perm:[2,3,0,1] row_mask:0xf bank_mask:0xf bound_ctrl:1
	ds_read_b128 v[28:31], v9 offset:23616
	ds_read_b32 v32, v10 offset:24128
	v_add_f32_dpp v52, v52, v52 row_half_mirror row_mask:0xf bank_mask:0xf bound_ctrl:1
	v_pk_mul_f32 v[26:27], v[6:7], v[42:43]
	v_add_f32_dpp v34, v25, v25 row_ror:8 row_mask:0xf bank_mask:0x3
	v_add_f32_dpp v52, v52, v52 row_mirror row_mask:0xf bank_mask:0xf bound_ctrl:1
	v_pk_fma_f32 v[6:7], v[106:107], v[52:53], v[56:57] op_sel_hi:[1,0,1]
	v_pk_fma_f32 v[26:27], v[4:5], v[40:41], v[26:27]
	v_pk_fma_f32 v[4:5], v[104:105], v[52:53], v[54:55] op_sel_hi:[1,0,1]
	ds_read_b128 v[36:39], v9 offset:22528
	ds_read_b128 v[48:51], v9 offset:23360
	v_add_f32_e32 v25, v26, v27
	v_add_f32_dpp v253, v8, v255 quad_perm:[2,3,0,1] row_mask:0xf bank_mask:0xf bound_ctrl:1
	v_pk_mul_f32 v[52:53], v[6:7], v[78:79]
	v_pk_mul_f32 v[56:57], v[6:7], v[82:83]
	v_pk_fma_f32 v[52:53], v[4:5], v[76:77], v[52:53]
	v_pk_mul_f32 v[54:55], v[4:5], v[80:81]
	v_add_f32_e32 v52, v52, v53
	ds_read_b128 v[68:71], v9 offset:24448
	ds_read_b128 v[72:75], v9 offset:24192
	v_add_f32_dpp v52, v52, v52 quad_perm:[1,0,3,2] row_mask:0xf bank_mask:0xf bound_ctrl:1
	v_pk_fma_f32 v[56:57], v[90:91], v[94:95], v[56:57] op_sel_hi:[1,0,1]
	v_pk_fma_f32 v[54:55], v[88:89], v[94:95], v[54:55] op_sel_hi:[1,0,1]
	v_add_f32_dpp v52, v52, v52 quad_perm:[2,3,0,1] row_mask:0xf bank_mask:0xf bound_ctrl:1
	ds_read_b128 v[84:87], v9 offset:24960
	ds_read_b32 v92, v10 offset:25472
	v_add_f32_dpp v52, v52, v52 row_half_mirror row_mask:0xf bank_mask:0xf bound_ctrl:1
	v_pk_mul_f32 v[26:27], v[6:7], v[98:99]
	v_add_f32_dpp v34, v25, v25 row_ror:8 row_mask:0xf bank_mask:0xc
	v_add_f32_dpp v52, v52, v52 row_mirror row_mask:0xf bank_mask:0xf bound_ctrl:1
	v_pk_fma_f32 v[6:7], v[110:111], v[52:53], v[56:57] op_sel_hi:[1,0,1]
	v_pk_fma_f32 v[26:27], v[4:5], v[96:97], v[26:27]
	v_pk_fma_f32 v[4:5], v[108:109], v[52:53], v[54:55] op_sel_hi:[1,0,1]
	ds_read_b128 v[40:43], v9 offset:23872
	ds_read_b128 v[104:107], v9 offset:24704
	v_add_f32_e32 v25, v26, v27
	v_add_f32_dpp v11, v34, v34 row_half_mirror row_mask:0xf bank_mask:0x5
	s_waitcnt lgkmcnt(6)
; __device__ void scan_block(const Params& P, int sb, unsigned char* lds) {
;     ...
;       for (int s = 0; s < SC_CH; ++s) {
;         f32x4 w4n, k4n, b4n, kh4n, r4n; float vn;
;         if (s + 1 < SC_CH) {
;           const float* qn = q + (s + 1) * SC_STEP;
;           w4n = *(const f32x4*)(qn); k4n = *(const f32x4*)(qn + 64); b4n = *(const f32x4*)(qn + 128); kh4n = *(const f32x4*)(qn + 192); r4n = *(const f32x4*)(qn + 256);
;           vn = qv[(s + 1) * SC_STEP];
;         }
;         __builtin_amdgcn_sched_barrier(0);
;         if (s > 0) {
;           const float y = dpp_allreduce16(ypart);
;           yk = (ks == ((s - 1) & 15)) ? y : yk;
;           if (((s - 1) & 15) == 15) yo[(size_t)(s - 16) * 1024] = yk;
;         }
;         const f32x2 pp = (f32x2){S[0], S[1]} * (f32x2){k4[0], k4[1]} + (f32x2){S[2], S[3]} * (f32x2){k4[2], k4[3]};
;         const f32x4 A = S * w4 + v * kh4;
;         const float ar = dpp_allreduce16(pp.x + pp.y);
;         S = A + ar * b4;
;         const f32x2 yy = (f32x2){S[0], S[1]} * (f32x2){r4[0], r4[1]} + (f32x2){S[2], S[3]} * (f32x2){r4[2], r4[3]};
;         ypart = yy.x + yy.y;
;         if (s + 1 < SC_CH) { w4 = w4n; k4 = k4n; b4 = b4n; kh4 = kh4n; r4 = r4n; v = vn; }
	v_pk_mul_f32 v[52:53], v[6:7], v[14:15]
	v_pk_mul_f32 v[56:57], v[6:7], v[18:19]
	v_pk_fma_f32 v[52:53], v[4:5], v[12:13], v[52:53]
	v_pk_mul_f32 v[54:55], v[4:5], v[16:17]
	v_add_f32_e32 v52, v52, v53
	ds_read_b128 v[76:79], v9 offset:25792
	ds_read_b128 v[80:83], v9 offset:25536
	v_add_f32_dpp v52, v52, v52 quad_perm:[1,0,3,2] row_mask:0xf bank_mask:0xf bound_ctrl:1
	v_pk_fma_f32 v[56:57], v[22:23], v[24:25], v[56:57] op_sel_hi:[1,0,1]
	v_pk_fma_f32 v[54:55], v[20:21], v[24:25], v[54:55] op_sel_hi:[1,0,1]
	v_add_f32_dpp v52, v52, v52 quad_perm:[2,3,0,1] row_mask:0xf bank_mask:0xf bound_ctrl:1
	ds_read_b128 v[88:91], v9 offset:26304
	ds_read_b32 v94, v10 offset:26816
	v_add_f32_dpp v52, v52, v52 row_half_mirror row_mask:0xf bank_mask:0xf bound_ctrl:1
	v_pk_mul_f32 v[26:27], v[6:7], v[102:103]
	v_add_f32_dpp v34, v25, v25 row_ror:8 row_mask:0xf bank_mask:0x3
	v_add_f32_dpp v52, v52, v52 row_mirror row_mask:0xf bank_mask:0xf bound_ctrl:1
	v_pk_fma_f32 v[6:7], v[46:47], v[52:53], v[56:57] op_sel_hi:[1,0,1]
	v_pk_fma_f32 v[26:27], v[4:5], v[100:101], v[26:27]
	v_pk_fma_f32 v[4:5], v[44:45], v[52:53], v[54:55] op_sel_hi:[1,0,1]
	ds_read_b128 v[96:99], v9 offset:25216
	ds_read_b128 v[108:111], v9 offset:26048
	v_add_f32_e32 v25, v26, v27
	v_pk_mul_f32 v[52:53], v[6:7], v[62:63]
	v_pk_mul_f32 v[56:57], v[6:7], v[66:67]
	v_pk_fma_f32 v[52:53], v[4:5], v[60:61], v[52:53]
	v_pk_mul_f32 v[54:55], v[4:5], v[64:65]
	v_add_f32_e32 v52, v52, v53
	ds_read_b128 v[12:15], v9 offset:27136
	ds_read_b128 v[16:19], v9 offset:26880
	v_add_f32_dpp v52, v52, v52 quad_perm:[1,0,3,2] row_mask:0xf bank_mask:0xf bound_ctrl:1
	v_pk_fma_f32 v[56:57], v[30:31], v[32:33], v[56:57] op_sel_hi:[1,0,1]
	v_pk_fma_f32 v[54:55], v[28:29], v[32:33], v[54:55] op_sel_hi:[1,0,1]
	v_add_f32_dpp v52, v52, v52 quad_perm:[2,3,0,1] row_mask:0xf bank_mask:0xf bound_ctrl:1
	ds_read_b128 v[20:23], v9 offset:27648
	ds_read_b32 v24, v10 offset:28160
	v_add_f32_dpp v52, v52, v52 row_half_mirror row_mask:0xf bank_mask:0xf bound_ctrl:1
	v_pk_mul_f32 v[26:27], v[6:7], v[38:39]
	v_add_f32_dpp v34, v25, v25 row_ror:8 row_mask:0xf bank_mask:0xc
	v_add_f32_dpp v52, v52, v52 row_mirror row_mask:0xf bank_mask:0xf bound_ctrl:1
	v_pk_fma_f32 v[6:7], v[50:51], v[52:53], v[56:57] op_sel_hi:[1,0,1]
	v_pk_fma_f32 v[26:27], v[4:5], v[36:37], v[26:27]
	v_pk_fma_f32 v[4:5], v[48:49], v[52:53], v[54:55] op_sel_hi:[1,0,1]
	ds_read_b128 v[100:103], v9 offset:26560
	ds_read_b128 v[44:47], v9 offset:27392
	v_add_f32_e32 v25, v26, v27
	v_add_f32_dpp v11, v34, v34 row_half_mirror row_mask:0xf bank_mask:0xa
	s_waitcnt lgkmcnt(6)
	v_pk_mul_f32 v[52:53], v[6:7], v[70:71]
	v_pk_mul_f32 v[56:57], v[6:7], v[74:75]
	v_pk_fma_f32 v[52:53], v[4:5], v[68:69], v[52:53]
	v_pk_mul_f32 v[54:55], v[4:5], v[72:73]
	v_add_f32_e32 v52, v52, v53
	ds_read_b128 v[60:63], v9 offset:28480
	ds_read_b128 v[64:67], v9 offset:28224
	v_add_f32_dpp v52, v52, v52 quad_perm:[1,0,3,2] row_mask:0xf bank_mask:0xf bound_ctrl:1
	v_pk_fma_f32 v[56:57], v[86:87], v[92:93], v[56:57] op_sel_hi:[1,0,1]
	v_pk_fma_f32 v[54:55], v[84:85], v[92:93], v[54:55] op_sel_hi:[1,0,1]
	v_add_f32_dpp v52, v52, v52 quad_perm:[2,3,0,1] row_mask:0xf bank_mask:0xf bound_ctrl:1
	ds_read_b128 v[28:31], v9 offset:28992
	ds_read_b32 v32, v10 offset:29504
	v_add_f32_dpp v52, v52, v52 row_half_mirror row_mask:0xf bank_mask:0xf bound_ctrl:1
	v_pk_mul_f32 v[26:27], v[6:7], v[42:43]
	v_add_f32_dpp v34, v25, v25 row_ror:8 row_mask:0xf bank_mask:0x3
	v_add_f32_dpp v52, v52, v52 row_mirror row_mask:0xf bank_mask:0xf bound_ctrl:1
	v_pk_fma_f32 v[6:7], v[106:107], v[52:53], v[56:57] op_sel_hi:[1,0,1]
	v_pk_fma_f32 v[26:27], v[4:5], v[40:41], v[26:27]
	v_pk_fma_f32 v[4:5], v[104:105], v[52:53], v[54:55] op_sel_hi:[1,0,1]
	ds_read_b128 v[36:39], v9 offset:27904
	ds_read_b128 v[48:51], v9 offset:28736
	v_add_f32_e32 v25, v26, v27
	v_cndmask_b32_e64 v255, v0, v11, s[40:41]
	v_pk_mul_f32 v[52:53], v[6:7], v[78:79]
	v_pk_mul_f32 v[56:57], v[6:7], v[82:83]
	v_pk_fma_f32 v[52:53], v[4:5], v[76:77], v[52:53]
	v_pk_mul_f32 v[54:55], v[4:5], v[80:81]
	v_add_f32_e32 v52, v52, v53
	ds_read_b128 v[68:71], v9 offset:29824
	ds_read_b128 v[72:75], v9 offset:29568
	v_add_f32_dpp v52, v52, v52 quad_perm:[1,0,3,2] row_mask:0xf bank_mask:0xf bound_ctrl:1
	v_pk_fma_f32 v[56:57], v[90:91], v[94:95], v[56:57] op_sel_hi:[1,0,1]
	v_pk_fma_f32 v[54:55], v[88:89], v[94:95], v[54:55] op_sel_hi:[1,0,1]
	v_add_f32_dpp v52, v52, v52 quad_perm:[2,3,0,1] row_mask:0xf bank_mask:0xf bound_ctrl:1
	ds_read_b128 v[84:87], v9 offset:30336
	ds_read_b32 v92, v10 offset:30848
	v_add_f32_dpp v52, v52, v52 row_half_mirror row_mask:0xf bank_mask:0xf bound_ctrl:1
	v_pk_mul_f32 v[26:27], v[6:7], v[98:99]
	v_add_f32_dpp v34, v25, v25 row_ror:8 row_mask:0xf bank_mask:0xc
	v_add_f32_dpp v52, v52, v52 row_mirror row_mask:0xf bank_mask:0xf bound_ctrl:1
	v_pk_fma_f32 v[6:7], v[110:111], v[52:53], v[56:57] op_sel_hi:[1,0,1]
	v_pk_fma_f32 v[26:27], v[4:5], v[96:97], v[26:27]
	v_pk_fma_f32 v[4:5], v[108:109], v[52:53], v[54:55] op_sel_hi:[1,0,1]
	ds_read_b128 v[40:43], v9 offset:29248
	ds_read_b128 v[104:107], v9 offset:30080
	v_add_f32_e32 v25, v26, v27
	v_add_f32_dpp v35, v34, v34 row_half_mirror row_mask:0xf bank_mask:0x5
	s_waitcnt lgkmcnt(6)
; __device__ void scan_block(const Params& P, int sb, unsigned char* lds) {
;     ...
;       for (int s = 0; s < SC_CH; ++s) {
;         f32x4 w4n, k4n, b4n, kh4n, r4n; float vn;
;         if (s + 1 < SC_CH) {
;           const float* qn = q + (s + 1) * SC_STEP;
;           w4n = *(const f32x4*)(qn); k4n = *(const f32x4*)(qn + 64); b4n = *(const f32x4*)(qn + 128); kh4n = *(const f32x4*)(qn + 192); r4n = *(const f32x4*)(qn + 256);
;           vn = qv[(s + 1) * SC_STEP];
;         }
;         __builtin_amdgcn_sched_barrier(0);
;         if (s > 0) {
;           const float y = dpp_allreduce16(ypart);
;           yk = (ks == ((s - 1) & 15)) ? y : yk;
;           if (((s - 1) & 15) == 15) yo[(size_t)(s - 16) * 1024] = yk;
;         }
;         const f32x2 pp = (f32x2){S[0], S[1]} * (f32x2){k4[0], k4[1]} + (f32x2){S[2], S[3]} * (f32x2){k4[2], k4[3]};
;         const f32x4 A = S * w4 + v * kh4;
;         const float ar = dpp_allreduce16(pp.x + pp.y);
;         S = A + ar * b4;
;         const f32x2 yy = (f32x2){S[0], S[1]} * (f32x2){r4[0], r4[1]} + (f32x2){S[2], S[3]} * (f32x2){r4[2], r4[3]};
;         ypart = yy.x + yy.y;
;         if (s + 1 < SC_CH) { w4 = w4n; k4 = k4n; b4 = b4n; kh4 = kh4n; r4 = r4n; v = vn; }
	v_pk_mul_f32 v[52:53], v[6:7], v[14:15]
	v_pk_mul_f32 v[56:57], v[6:7], v[18:19]
	v_pk_fma_f32 v[52:53], v[4:5], v[12:13], v[52:53]
	v_pk_mul_f32 v[54:55], v[4:5], v[16:17]
	v_add_f32_e32 v52, v52, v53
	ds_read_b128 v[76:79], v9 offset:31168
	ds_read_b128 v[80:83], v9 offset:30912
	v_add_f32_dpp v52, v52, v52 quad_perm:[1,0,3,2] row_mask:0xf bank_mask:0xf bound_ctrl:1
	v_pk_fma_f32 v[56:57], v[22:23], v[24:25], v[56:57] op_sel_hi:[1,0,1]
	v_pk_fma_f32 v[54:55], v[20:21], v[24:25], v[54:55] op_sel_hi:[1,0,1]
	v_add_f32_dpp v52, v52, v52 quad_perm:[2,3,0,1] row_mask:0xf bank_mask:0xf bound_ctrl:1
	ds_read_b128 v[88:91], v9 offset:31680
	ds_read_b32 v94, v10 offset:32192
	v_add_f32_dpp v52, v52, v52 row_half_mirror row_mask:0xf bank_mask:0xf bound_ctrl:1
	v_pk_mul_f32 v[26:27], v[6:7], v[102:103]
	v_add_f32_dpp v34, v25, v25 row_ror:8 row_mask:0xf bank_mask:0x3
	v_add_f32_dpp v52, v52, v52 row_mirror row_mask:0xf bank_mask:0xf bound_ctrl:1
	v_pk_fma_f32 v[6:7], v[46:47], v[52:53], v[56:57] op_sel_hi:[1,0,1]
	v_pk_fma_f32 v[26:27], v[4:5], v[100:101], v[26:27]
	v_pk_fma_f32 v[4:5], v[44:45], v[52:53], v[54:55] op_sel_hi:[1,0,1]
	ds_read_b128 v[96:99], v9 offset:30592
	ds_read_b128 v[108:111], v9 offset:31424
	v_add_f32_e32 v25, v26, v27
	v_cndmask_b32_e64 v8, v11, v0, s[40:41]
	v_pk_mul_f32 v[52:53], v[6:7], v[62:63]
	v_pk_mul_f32 v[56:57], v[6:7], v[66:67]
	v_pk_fma_f32 v[52:53], v[4:5], v[60:61], v[52:53]
	v_pk_mul_f32 v[54:55], v[4:5], v[64:65]
	v_add_f32_e32 v52, v52, v53
	ds_read_b128 v[12:15], v9 offset:32512
	ds_read_b128 v[16:19], v9 offset:32256
	v_add_f32_dpp v52, v52, v52 quad_perm:[1,0,3,2] row_mask:0xf bank_mask:0xf bound_ctrl:1
	v_pk_fma_f32 v[56:57], v[30:31], v[32:33], v[56:57] op_sel_hi:[1,0,1]
	v_pk_fma_f32 v[54:55], v[28:29], v[32:33], v[54:55] op_sel_hi:[1,0,1]
	v_add_f32_dpp v52, v52, v52 quad_perm:[2,3,0,1] row_mask:0xf bank_mask:0xf bound_ctrl:1
	ds_read_b128 v[20:23], v9 offset:33024
	ds_read_b32 v24, v10 offset:33536
	v_add_f32_dpp v52, v52, v52 row_half_mirror row_mask:0xf bank_mask:0xf bound_ctrl:1
	v_pk_mul_f32 v[26:27], v[6:7], v[38:39]
	v_add_f32_dpp v34, v25, v25 row_ror:8 row_mask:0xf bank_mask:0xc
	v_add_f32_dpp v52, v52, v52 row_mirror row_mask:0xf bank_mask:0xf bound_ctrl:1
	v_pk_fma_f32 v[6:7], v[50:51], v[52:53], v[56:57] op_sel_hi:[1,0,1]
	v_pk_fma_f32 v[26:27], v[4:5], v[36:37], v[26:27]
	v_pk_fma_f32 v[4:5], v[48:49], v[52:53], v[54:55] op_sel_hi:[1,0,1]
	ds_read_b128 v[100:103], v9 offset:31936
	ds_read_b128 v[44:47], v9 offset:32768
	v_add_f32_e32 v25, v26, v27
	v_add_f32_dpp v35, v34, v34 row_half_mirror row_mask:0xf bank_mask:0xa
	s_waitcnt lgkmcnt(6)
	v_pk_mul_f32 v[52:53], v[6:7], v[70:71]
	v_pk_mul_f32 v[56:57], v[6:7], v[74:75]
	v_pk_fma_f32 v[52:53], v[4:5], v[68:69], v[52:53]
	v_pk_mul_f32 v[54:55], v[4:5], v[72:73]
	v_add_f32_e32 v52, v52, v53
	ds_read_b128 v[60:63], v9 offset:33856
	ds_read_b128 v[64:67], v9 offset:33600
	v_add_f32_dpp v52, v52, v52 quad_perm:[1,0,3,2] row_mask:0xf bank_mask:0xf bound_ctrl:1
	v_pk_fma_f32 v[56:57], v[86:87], v[92:93], v[56:57] op_sel_hi:[1,0,1]
	v_pk_fma_f32 v[54:55], v[84:85], v[92:93], v[54:55] op_sel_hi:[1,0,1]
	v_add_f32_dpp v52, v52, v52 quad_perm:[2,3,0,1] row_mask:0xf bank_mask:0xf bound_ctrl:1
	ds_read_b128 v[28:31], v9 offset:34368
	ds_read_b32 v32, v10 offset:34880
	v_add_f32_dpp v52, v52, v52 row_half_mirror row_mask:0xf bank_mask:0xf bound_ctrl:1
	v_pk_mul_f32 v[26:27], v[6:7], v[42:43]
	v_add_f32_dpp v34, v25, v25 row_ror:8 row_mask:0xf bank_mask:0x3
	v_add_f32_dpp v52, v52, v52 row_mirror row_mask:0xf bank_mask:0xf bound_ctrl:1
	v_pk_fma_f32 v[6:7], v[106:107], v[52:53], v[56:57] op_sel_hi:[1,0,1]
	v_pk_fma_f32 v[26:27], v[4:5], v[40:41], v[26:27]
	v_pk_fma_f32 v[4:5], v[104:105], v[52:53], v[54:55] op_sel_hi:[1,0,1]
	ds_read_b128 v[36:39], v9 offset:33280
	ds_read_b128 v[48:51], v9 offset:34112
	v_add_f32_e32 v25, v26, v27
	v_add_f32_dpp v254, v8, v255 quad_perm:[2,3,0,1] row_mask:0xf bank_mask:0xf bound_ctrl:1
	v_pk_mul_f32 v[52:53], v[6:7], v[78:79]
	v_pk_mul_f32 v[56:57], v[6:7], v[82:83]
	v_pk_fma_f32 v[52:53], v[4:5], v[76:77], v[52:53]
	v_pk_mul_f32 v[54:55], v[4:5], v[80:81]
	v_add_f32_e32 v52, v52, v53
	ds_read_b128 v[68:71], v9 offset:35200
	ds_read_b128 v[72:75], v9 offset:34944
	v_add_f32_dpp v52, v52, v52 quad_perm:[1,0,3,2] row_mask:0xf bank_mask:0xf bound_ctrl:1
	v_pk_fma_f32 v[56:57], v[90:91], v[94:95], v[56:57] op_sel_hi:[1,0,1]
	v_pk_fma_f32 v[54:55], v[88:89], v[94:95], v[54:55] op_sel_hi:[1,0,1]
	v_add_f32_dpp v52, v52, v52 quad_perm:[2,3,0,1] row_mask:0xf bank_mask:0xf bound_ctrl:1
	ds_read_b128 v[84:87], v9 offset:35712
	ds_read_b32 v92, v10 offset:36224
	v_add_f32_dpp v52, v52, v52 row_half_mirror row_mask:0xf bank_mask:0xf bound_ctrl:1
	v_pk_mul_f32 v[26:27], v[6:7], v[98:99]
	v_add_f32_dpp v34, v25, v25 row_ror:8 row_mask:0xf bank_mask:0xc
	v_add_f32_dpp v52, v52, v52 row_mirror row_mask:0xf bank_mask:0xf bound_ctrl:1
	v_pk_fma_f32 v[6:7], v[110:111], v[52:53], v[56:57] op_sel_hi:[1,0,1]
	v_pk_fma_f32 v[26:27], v[4:5], v[96:97], v[26:27]
	v_pk_fma_f32 v[4:5], v[108:109], v[52:53], v[54:55] op_sel_hi:[1,0,1]
	ds_read_b128 v[40:43], v9 offset:34624
	ds_read_b128 v[104:107], v9 offset:35456
	v_add_f32_e32 v25, v26, v27
	v_add_f32_dpp v58, v34, v34 row_half_mirror row_mask:0xf bank_mask:0x5
	s_waitcnt lgkmcnt(6)
; __device__ void scan_block(const Params& P, int sb, unsigned char* lds) {
;     ...
;       for (int s = 0; s < SC_CH; ++s) {
;         f32x4 w4n, k4n, b4n, kh4n, r4n; float vn;
;         if (s + 1 < SC_CH) {
;           const float* qn = q + (s + 1) * SC_STEP;
;           w4n = *(const f32x4*)(qn); k4n = *(const f32x4*)(qn + 64); b4n = *(const f32x4*)(qn + 128); kh4n = *(const f32x4*)(qn + 192); r4n = *(const f32x4*)(qn + 256);
;           vn = qv[(s + 1) * SC_STEP];
;         }
;         __builtin_amdgcn_sched_barrier(0);
;         if (s > 0) {
;           const float y = dpp_allreduce16(ypart);
;           yk = (ks == ((s - 1) & 15)) ? y : yk;
;           if (((s - 1) & 15) == 15) yo[(size_t)(s - 16) * 1024] = yk;
;         }
;         const f32x2 pp = (f32x2){S[0], S[1]} * (f32x2){k4[0], k4[1]} + (f32x2){S[2], S[3]} * (f32x2){k4[2], k4[3]};
;         const f32x4 A = S * w4 + v * kh4;
;         const float ar = dpp_allreduce16(pp.x + pp.y);
;         S = A + ar * b4;
;         const f32x2 yy = (f32x2){S[0], S[1]} * (f32x2){r4[0], r4[1]} + (f32x2){S[2], S[3]} * (f32x2){r4[2], r4[3]};
;         ypart = yy.x + yy.y;
;         if (s + 1 < SC_CH) { w4 = w4n; k4 = k4n; b4 = b4n; kh4 = kh4n; r4 = r4n; v = vn; }
	v_pk_mul_f32 v[52:53], v[6:7], v[14:15]
	v_pk_mul_f32 v[56:57], v[6:7], v[18:19]
	v_pk_fma_f32 v[52:53], v[4:5], v[12:13], v[52:53]
	v_pk_mul_f32 v[54:55], v[4:5], v[16:17]
	v_add_f32_e32 v52, v52, v53
	ds_read_b128 v[76:79], v9 offset:36544
	ds_read_b128 v[80:83], v9 offset:36288
	v_add_f32_dpp v52, v52, v52 quad_perm:[1,0,3,2] row_mask:0xf bank_mask:0xf bound_ctrl:1
	v_pk_fma_f32 v[56:57], v[22:23], v[24:25], v[56:57] op_sel_hi:[1,0,1]
	v_pk_fma_f32 v[54:55], v[20:21], v[24:25], v[54:55] op_sel_hi:[1,0,1]
	v_add_f32_dpp v52, v52, v52 quad_perm:[2,3,0,1] row_mask:0xf bank_mask:0xf bound_ctrl:1
	ds_read_b128 v[88:91], v9 offset:37056
	ds_read_b32 v94, v10 offset:37568
	v_add_f32_dpp v52, v52, v52 row_half_mirror row_mask:0xf bank_mask:0xf bound_ctrl:1
	v_pk_mul_f32 v[26:27], v[6:7], v[102:103]
	v_add_f32_dpp v34, v25, v25 row_ror:8 row_mask:0xf bank_mask:0x3
	v_add_f32_dpp v52, v52, v52 row_mirror row_mask:0xf bank_mask:0xf bound_ctrl:1
	v_pk_fma_f32 v[6:7], v[46:47], v[52:53], v[56:57] op_sel_hi:[1,0,1]
	v_pk_fma_f32 v[26:27], v[4:5], v[100:101], v[26:27]
	v_pk_fma_f32 v[4:5], v[44:45], v[52:53], v[54:55] op_sel_hi:[1,0,1]
	ds_read_b128 v[96:99], v9 offset:35968
	ds_read_b128 v[108:111], v9 offset:36800
	v_add_f32_e32 v25, v26, v27
	v_cndmask_b32_e64 v255, v253, v254, s[42:43]
	v_pk_mul_f32 v[52:53], v[6:7], v[62:63]
	v_pk_mul_f32 v[56:57], v[6:7], v[66:67]
	v_pk_fma_f32 v[52:53], v[4:5], v[60:61], v[52:53]
	v_pk_mul_f32 v[54:55], v[4:5], v[64:65]
	v_add_f32_e32 v52, v52, v53
	ds_read_b128 v[12:15], v9 offset:37888
	ds_read_b128 v[16:19], v9 offset:37632
	v_add_f32_dpp v52, v52, v52 quad_perm:[1,0,3,2] row_mask:0xf bank_mask:0xf bound_ctrl:1
	v_pk_fma_f32 v[56:57], v[30:31], v[32:33], v[56:57] op_sel_hi:[1,0,1]
	v_pk_fma_f32 v[54:55], v[28:29], v[32:33], v[54:55] op_sel_hi:[1,0,1]
	v_add_f32_dpp v52, v52, v52 quad_perm:[2,3,0,1] row_mask:0xf bank_mask:0xf bound_ctrl:1
	ds_read_b128 v[20:23], v9 offset:38400
	ds_read_b32 v24, v10 offset:38912
	v_add_f32_dpp v52, v52, v52 row_half_mirror row_mask:0xf bank_mask:0xf bound_ctrl:1
	v_pk_mul_f32 v[26:27], v[6:7], v[38:39]
	v_add_f32_dpp v34, v25, v25 row_ror:8 row_mask:0xf bank_mask:0xc
	v_add_f32_dpp v52, v52, v52 row_mirror row_mask:0xf bank_mask:0xf bound_ctrl:1
	v_pk_fma_f32 v[6:7], v[50:51], v[52:53], v[56:57] op_sel_hi:[1,0,1]
	v_pk_fma_f32 v[26:27], v[4:5], v[36:37], v[26:27]
	v_pk_fma_f32 v[4:5], v[48:49], v[52:53], v[54:55] op_sel_hi:[1,0,1]
	ds_read_b128 v[100:103], v9 offset:37312
	ds_read_b128 v[44:47], v9 offset:38144
	v_add_f32_e32 v25, v26, v27
	v_add_f32_dpp v58, v34, v34 row_half_mirror row_mask:0xf bank_mask:0xa
	s_waitcnt lgkmcnt(6)
	v_pk_mul_f32 v[52:53], v[6:7], v[70:71]
	v_pk_mul_f32 v[56:57], v[6:7], v[74:75]
	v_pk_fma_f32 v[52:53], v[4:5], v[68:69], v[52:53]
	v_pk_mul_f32 v[54:55], v[4:5], v[72:73]
	v_add_f32_e32 v52, v52, v53
	ds_read_b128 v[60:63], v9 offset:39232
	ds_read_b128 v[64:67], v9 offset:38976
	v_add_f32_dpp v52, v52, v52 quad_perm:[1,0,3,2] row_mask:0xf bank_mask:0xf bound_ctrl:1
	v_pk_fma_f32 v[56:57], v[86:87], v[92:93], v[56:57] op_sel_hi:[1,0,1]
	v_pk_fma_f32 v[54:55], v[84:85], v[92:93], v[54:55] op_sel_hi:[1,0,1]
	v_add_f32_dpp v52, v52, v52 quad_perm:[2,3,0,1] row_mask:0xf bank_mask:0xf bound_ctrl:1
	ds_read_b128 v[28:31], v9 offset:39744
	ds_read_b32 v32, v10 offset:40256
	v_add_f32_dpp v52, v52, v52 row_half_mirror row_mask:0xf bank_mask:0xf bound_ctrl:1
	v_pk_mul_f32 v[26:27], v[6:7], v[42:43]
	v_add_f32_dpp v34, v25, v25 row_ror:8 row_mask:0xf bank_mask:0x3
	v_add_f32_dpp v52, v52, v52 row_mirror row_mask:0xf bank_mask:0xf bound_ctrl:1
	v_pk_fma_f32 v[6:7], v[106:107], v[52:53], v[56:57] op_sel_hi:[1,0,1]
	v_pk_fma_f32 v[26:27], v[4:5], v[40:41], v[26:27]
	v_pk_fma_f32 v[4:5], v[104:105], v[52:53], v[54:55] op_sel_hi:[1,0,1]
	ds_read_b128 v[36:39], v9 offset:38656
	ds_read_b128 v[48:51], v9 offset:39488
	v_add_f32_e32 v25, v26, v27
	v_cndmask_b32_e64 v8, v254, v253, s[42:43]
	v_pk_mul_f32 v[52:53], v[6:7], v[78:79]
	v_pk_mul_f32 v[56:57], v[6:7], v[82:83]
	v_pk_fma_f32 v[52:53], v[4:5], v[76:77], v[52:53]
	v_pk_mul_f32 v[54:55], v[4:5], v[80:81]
	v_add_f32_e32 v52, v52, v53
	ds_read_b128 v[68:71], v9 offset:40576
	ds_read_b128 v[72:75], v9 offset:40320
	v_add_f32_dpp v52, v52, v52 quad_perm:[1,0,3,2] row_mask:0xf bank_mask:0xf bound_ctrl:1
	v_pk_fma_f32 v[56:57], v[90:91], v[94:95], v[56:57] op_sel_hi:[1,0,1]
	v_pk_fma_f32 v[54:55], v[88:89], v[94:95], v[54:55] op_sel_hi:[1,0,1]
	v_add_f32_dpp v52, v52, v52 quad_perm:[2,3,0,1] row_mask:0xf bank_mask:0xf bound_ctrl:1
	ds_read_b128 v[84:87], v9 offset:41088
	ds_read_b32 v92, v10 offset:41600
	v_add_f32_dpp v52, v52, v52 row_half_mirror row_mask:0xf bank_mask:0xf bound_ctrl:1
	v_pk_mul_f32 v[26:27], v[6:7], v[98:99]
	v_add_f32_dpp v34, v25, v25 row_ror:8 row_mask:0xf bank_mask:0xc
	v_add_f32_dpp v52, v52, v52 row_mirror row_mask:0xf bank_mask:0xf bound_ctrl:1
	v_pk_fma_f32 v[6:7], v[110:111], v[52:53], v[56:57] op_sel_hi:[1,0,1]
	v_pk_fma_f32 v[26:27], v[4:5], v[96:97], v[26:27]
	v_pk_fma_f32 v[4:5], v[108:109], v[52:53], v[54:55] op_sel_hi:[1,0,1]
	ds_read_b128 v[40:43], v9 offset:40000
	ds_read_b128 v[104:107], v9 offset:40832
	v_add_f32_e32 v25, v26, v27
	v_add_f32_dpp v0, v34, v34 row_half_mirror row_mask:0xf bank_mask:0x5
	s_waitcnt lgkmcnt(8)
; __device__ void scan_block(const Params& P, int sb, unsigned char* lds) {
;     ...
;       for (int s = 0; s < SC_CH; ++s) {
;         f32x4 w4n, k4n, b4n, kh4n, r4n; float vn;
;         if (s + 1 < SC_CH) {
;           const float* qn = q + (s + 1) * SC_STEP;
;           w4n = *(const f32x4*)(qn); k4n = *(const f32x4*)(qn + 64); b4n = *(const f32x4*)(qn + 128); kh4n = *(const f32x4*)(qn + 192); r4n = *(const f32x4*)(qn + 256);
;           vn = qv[(s + 1) * SC_STEP];
;         }
;         __builtin_amdgcn_sched_barrier(0);
;         if (s > 0) {
;           const float y = dpp_allreduce16(ypart);
;           yk = (ks == ((s - 1) & 15)) ? y : yk;
;           if (((s - 1) & 15) == 15) yo[(size_t)(s - 16) * 1024] = yk;
;         }
;         const f32x2 pp = (f32x2){S[0], S[1]} * (f32x2){k4[0], k4[1]} + (f32x2){S[2], S[3]} * (f32x2){k4[2], k4[3]};
;         const f32x4 A = S * w4 + v * kh4;
;         const float ar = dpp_allreduce16(pp.x + pp.y);
;         S = A + ar * b4;
;         const f32x2 yy = (f32x2){S[0], S[1]} * (f32x2){r4[0], r4[1]} + (f32x2){S[2], S[3]} * (f32x2){r4[2], r4[3]};
;         ypart = yy.x + yy.y;
;         if (s + 1 < SC_CH) { w4 = w4n; k4 = k4n; b4 = b4n; kh4 = kh4n; r4 = r4n; v = vn; }
;       }
;       { const float y = dpp_allreduce16(ypart); yk = (ks == 15) ? y : yk; yo[(size_t)16 * 1024] = yk; }
;       __syncthreads();
	v_pk_mul_f32 v[52:53], v[6:7], v[14:15]
	v_pk_mul_f32 v[56:57], v[6:7], v[18:19]
	v_pk_fma_f32 v[52:53], v[4:5], v[12:13], v[52:53]
	v_pk_mul_f32 v[54:55], v[4:5], v[16:17]
	v_add_f32_e32 v52, v52, v53
	ds_read_b128 v[76:79], v9 offset:41920
	ds_read_b128 v[80:83], v9 offset:41664
	v_add_f32_dpp v52, v52, v52 quad_perm:[1,0,3,2] row_mask:0xf bank_mask:0xf bound_ctrl:1
	v_pk_fma_f32 v[56:57], v[22:23], v[24:25], v[56:57] op_sel_hi:[1,0,1]
	v_pk_fma_f32 v[54:55], v[20:21], v[24:25], v[54:55] op_sel_hi:[1,0,1]
	v_add_f32_dpp v52, v52, v52 quad_perm:[2,3,0,1] row_mask:0xf bank_mask:0xf bound_ctrl:1
	ds_read_b128 v[88:91], v9 offset:42432
	ds_read_b32 v94, v10 offset:42944
	v_add_f32_dpp v52, v52, v52 row_half_mirror row_mask:0xf bank_mask:0xf bound_ctrl:1
	v_pk_mul_f32 v[26:27], v[6:7], v[102:103]
	v_add_f32_dpp v34, v25, v25 row_ror:8 row_mask:0xf bank_mask:0x3
	v_add_f32_dpp v52, v52, v52 row_mirror row_mask:0xf bank_mask:0xf bound_ctrl:1
	v_pk_fma_f32 v[6:7], v[46:47], v[52:53], v[56:57] op_sel_hi:[1,0,1]
	v_pk_fma_f32 v[26:27], v[4:5], v[100:101], v[26:27]
	v_pk_fma_f32 v[4:5], v[44:45], v[52:53], v[54:55] op_sel_hi:[1,0,1]
	ds_read_b128 v[96:99], v9 offset:41344
	ds_read_b128 v[100:103], v9 offset:42688
	ds_read_b128 v[108:111], v9 offset:42176
	v_add_f32_e32 v25, v26, v27
	v_add_f32_dpp v33, v8, v255 quad_perm:[1,0,3,2] row_mask:0xf bank_mask:0xf bound_ctrl:1
	v_pk_mul_f32 v[52:53], v[6:7], v[62:63]
	v_pk_mul_f32 v[56:57], v[6:7], v[66:67]
	v_pk_fma_f32 v[52:53], v[4:5], v[60:61], v[52:53]
	v_pk_mul_f32 v[54:55], v[4:5], v[64:65]
	v_add_f32_e32 v52, v52, v53
	s_nop 1
	v_add_f32_dpp v52, v52, v52 quad_perm:[1,0,3,2] row_mask:0xf bank_mask:0xf bound_ctrl:1
	v_pk_fma_f32 v[56:57], v[30:31], v[32:33], v[56:57] op_sel_hi:[1,0,1]
	v_pk_fma_f32 v[54:55], v[28:29], v[32:33], v[54:55] op_sel_hi:[1,0,1]
	v_add_f32_dpp v52, v52, v52 quad_perm:[2,3,0,1] row_mask:0xf bank_mask:0xf bound_ctrl:1
	s_waitcnt lgkmcnt(0)
	s_barrier
	v_xor_b32_e32 v9, 0xa800, v9
	v_xor_b32_e32 v10, 0xa800, v10
	ds_read_b128 v[12:15], v9 offset:256
	ds_read_b128 v[16:19], v9 offset:0
	ds_read_b128 v[20:23], v9 offset:768
	ds_read_b32 v24, v10 offset:1280
	v_add_f32_dpp v52, v52, v52 row_half_mirror row_mask:0xf bank_mask:0xf bound_ctrl:1
	v_pk_mul_f32 v[26:27], v[6:7], v[38:39]
	v_add_f32_dpp v34, v25, v25 row_ror:8 row_mask:0xf bank_mask:0xc
	v_add_f32_dpp v52, v52, v52 row_mirror row_mask:0xf bank_mask:0xf bound_ctrl:1
	v_pk_fma_f32 v[6:7], v[50:51], v[52:53], v[56:57] op_sel_hi:[1,0,1]
	v_pk_fma_f32 v[26:27], v[4:5], v[36:37], v[26:27]
	v_pk_fma_f32 v[4:5], v[48:49], v[52:53], v[54:55] op_sel_hi:[1,0,1]
	ds_read_b128 v[44:47], v9 offset:512
	v_add_f32_e32 v25, v26, v27
	v_add_f32_dpp v0, v34, v34 row_half_mirror row_mask:0xf bank_mask:0xa
	s_waitcnt lgkmcnt(5)
	v_pk_mul_f32 v[52:53], v[6:7], v[70:71]
	v_pk_mul_f32 v[56:57], v[6:7], v[74:75]
	v_pk_fma_f32 v[52:53], v[4:5], v[68:69], v[52:53]
	v_pk_mul_f32 v[54:55], v[4:5], v[72:73]
	v_add_f32_e32 v52, v52, v53
	ds_read_b128 v[60:63], v9 offset:1600
	ds_read_b128 v[64:67], v9 offset:1344
	v_add_f32_dpp v52, v52, v52 quad_perm:[1,0,3,2] row_mask:0xf bank_mask:0xf bound_ctrl:1
	v_pk_fma_f32 v[56:57], v[86:87], v[92:93], v[56:57] op_sel_hi:[1,0,1]
	v_pk_fma_f32 v[54:55], v[84:85], v[92:93], v[54:55] op_sel_hi:[1,0,1]
	v_add_f32_dpp v52, v52, v52 quad_perm:[2,3,0,1] row_mask:0xf bank_mask:0xf bound_ctrl:1
	ds_read_b128 v[28:31], v9 offset:2112
	ds_read_b32 v32, v10 offset:2624
	v_add_f32_dpp v52, v52, v52 row_half_mirror row_mask:0xf bank_mask:0xf bound_ctrl:1
	v_pk_mul_f32 v[26:27], v[6:7], v[42:43]
	v_add_f32_dpp v34, v25, v25 row_ror:8 row_mask:0xf bank_mask:0x3
	v_add_f32_dpp v52, v52, v52 row_mirror row_mask:0xf bank_mask:0xf bound_ctrl:1
	v_pk_fma_f32 v[6:7], v[106:107], v[52:53], v[56:57] op_sel_hi:[1,0,1]
	v_pk_fma_f32 v[26:27], v[4:5], v[40:41], v[26:27]
	v_pk_fma_f32 v[4:5], v[104:105], v[52:53], v[54:55] op_sel_hi:[1,0,1]
	ds_read_b128 v[36:39], v9 offset:1024
	ds_read_b128 v[48:51], v9 offset:1856
	v_add_f32_e32 v25, v26, v27
	global_store_dword v2, v33, s[4:5]
	v_pk_mul_f32 v[52:53], v[6:7], v[78:79]
	v_pk_mul_f32 v[56:57], v[6:7], v[82:83]
	v_pk_fma_f32 v[52:53], v[4:5], v[76:77], v[52:53]
	v_pk_mul_f32 v[54:55], v[4:5], v[80:81]
	v_add_f32_e32 v52, v52, v53
	ds_read_b128 v[68:71], v9 offset:2944
	ds_read_b128 v[72:75], v9 offset:2688
	v_add_f32_dpp v52, v52, v52 quad_perm:[1,0,3,2] row_mask:0xf bank_mask:0xf bound_ctrl:1
	v_pk_fma_f32 v[56:57], v[90:91], v[94:95], v[56:57] op_sel_hi:[1,0,1]
	v_pk_fma_f32 v[54:55], v[88:89], v[94:95], v[54:55] op_sel_hi:[1,0,1]
	v_add_f32_dpp v52, v52, v52 quad_perm:[2,3,0,1] row_mask:0xf bank_mask:0xf bound_ctrl:1
	ds_read_b128 v[84:87], v9 offset:3456
	ds_read_b32 v92, v10 offset:3968
	v_add_f32_dpp v52, v52, v52 row_half_mirror row_mask:0xf bank_mask:0xf bound_ctrl:1
	v_pk_mul_f32 v[26:27], v[6:7], v[98:99]
	v_add_f32_dpp v34, v25, v25 row_ror:8 row_mask:0xf bank_mask:0xc
	v_add_f32_dpp v52, v52, v52 row_mirror row_mask:0xf bank_mask:0xf bound_ctrl:1
	v_pk_fma_f32 v[6:7], v[110:111], v[52:53], v[56:57] op_sel_hi:[1,0,1]
	v_pk_fma_f32 v[26:27], v[4:5], v[96:97], v[26:27]
	v_pk_fma_f32 v[4:5], v[108:109], v[52:53], v[54:55] op_sel_hi:[1,0,1]
	ds_read_b128 v[40:43], v9 offset:2368
	ds_read_b128 v[104:107], v9 offset:3200
	v_add_f32_e32 v25, v26, v27
	v_add_f32_dpp v11, v34, v34 row_half_mirror row_mask:0xf bank_mask:0x5
	s_nop 0
	v_add_f32_dpp v34, v25, v25 row_ror:8 row_mask:0xf bank_mask:0x3
	v_pk_mul_f32 v[26:27], v[6:7], v[102:103]
	v_cndmask_b32_e64 v255, v35, v58, s[40:41]
	v_cndmask_b32_e64 v8, v58, v35, s[40:41]
	v_pk_fma_f32 v[26:27], v[4:5], v[100:101], v[26:27]
	s_nop 0
	v_add_f32_e32 v25, v26, v27
	v_add_f32_dpp v253, v8, v255 quad_perm:[2,3,0,1] row_mask:0xf bank_mask:0xf bound_ctrl:1
	s_nop 0
	v_add_f32_dpp v34, v25, v25 row_ror:8 row_mask:0xf bank_mask:0xc
	s_nop 1
	v_add_f32_dpp v11, v34, v34 row_half_mirror row_mask:0xf bank_mask:0xa
	s_nop 1
	v_cndmask_b32_e64 v255, v0, v11, s[40:41]
	v_cndmask_b32_e64 v8, v11, v0, s[40:41]
	s_nop 1
	v_add_f32_dpp v254, v8, v255 quad_perm:[2,3,0,1] row_mask:0xf bank_mask:0xf bound_ctrl:1
	v_cndmask_b32_e64 v255, v253, v254, s[42:43]
	v_cndmask_b32_e64 v8, v254, v253, s[42:43]
	s_add_i32 s3, s3, 1
	s_nop 0
	v_add_f32_dpp v33, v8, v255 quad_perm:[1,0,3,2] row_mask:0xf bank_mask:0xf bound_ctrl:1
	global_store_dword v3, v33, s[4:5]
	s_add_u32 s4, s4, 0x20000
	s_addc_u32 s5, s5, 0
	s_cmp_lg_u32 s3, 0x100
	s_cbranch_scc1 .Lscan_top
	s_waitcnt lgkmcnt(0)
	s_setprio 0
	v_readlane_b32 s60, v250, 1
	v_readlane_b32 s61, v250, 2
	s_mov_b64 s[62:63], s[90:91]
